# code placement: hot loop heads (10 GEMM k-loops, attention key loop) pinned at 0 mod 8 bytes
# speedup vs baseline: 1.0037x; 1.0037x over previous
.LBB0_263:
	s_ashr_i32 s21, s58, 2
	v_mov_b32_e32 v6, v181
	s_and_b32 s6, s58, 7
	s_and_b32 s21, s21, -8
	s_or_b32 s48, s21, s6
	v_lshrrev_b32_e32 v7, 4, v6
	v_lshlrev_b32_e32 v1, 6, v6
	v_xor_b32_e32 v0, v7, v6
	v_and_b32_e32 v8, 0x3c0, v1
	v_lshlrev_b32_e32 v1, 8, v6
	s_ashr_i32 s49, s48, 31
	v_lshlrev_b32_e32 v0, 3, v0
	v_and_b32_e32 v1, 0xfffff800, v1
	s_and_b32 s20, s57, 7
	s_bfe_u32 s6, s58, 0x20003
	s_lshl_b64 s[50:51], s[48:49], 20
	v_and_or_b32 v0, v0, 56, v1
	s_add_u32 s50, s3, s50
	v_ashrrev_i32_e32 v1, 31, v0
	s_addc_u32 s51, s54, s51
	v_lshlrev_b64 v[0:1], 1, v[0:1]
	v_lshl_add_u32 v135, v6, 4, 0
	v_lshl_add_u64 v[2:3], s[50:51], 0, v[0:1]
	v_readfirstlane_b32 s50, v135
	v_add_u32_e32 v9, 0x2000, v135
	s_mov_b32 m0, s50
	v_readfirstlane_b32 s50, v9
	v_add_u32_e32 v9, 0x4000, v135
	s_waitcnt lgkmcnt(0)
	s_barrier
	global_load_lds_dwordx4 v[2:3], off
	v_lshl_add_u64 v[4:5], v[2:3], 0, s[8:9]
	s_mov_b32 m0, s50
	v_readfirstlane_b32 s50, v9
	global_load_lds_dwordx4 v[4:5], off
	v_lshl_add_u64 v[4:5], v[2:3], 0, s[10:11]
	s_mov_b32 m0, s50
	s_lshl_b32 s49, s6, 20
	global_load_lds_dwordx4 v[4:5], off
	v_add_u32_e32 v4, 0x6000, v135
	s_add_u32 s52, s55, s49
	v_readfirstlane_b32 s50, v4
	v_add_u32_e32 v4, 0x8000, v135
	s_addc_u32 s53, s56, 0
	v_lshl_add_u64 v[2:3], v[2:3], 0, s[12:13]
	s_mov_b32 m0, s50
	v_readfirstlane_b32 s50, v4
	v_add_u32_e32 v9, 0xa000, v135
	global_load_lds_dwordx4 v[2:3], off
	v_lshl_add_u64 v[2:3], s[52:53], 0, v[0:1]
	s_mov_b32 m0, s50
	v_readfirstlane_b32 s50, v9
	v_add_u32_e32 v9, 0xc000, v135
	global_load_lds_dwordx4 v[2:3], off
	v_lshl_add_u64 v[4:5], v[2:3], 0, s[8:9]
	s_mov_b32 m0, s50
	v_readfirstlane_b32 s50, v9
	global_load_lds_dwordx4 v[4:5], off
	v_lshl_add_u64 v[4:5], v[2:3], 0, s[10:11]
	s_mov_b32 m0, s50
	v_lshl_add_u64 v[2:3], v[2:3], 0, s[12:13]
	global_load_lds_dwordx4 v[4:5], off
	v_add_u32_e32 v4, 0xe000, v135
	v_mov_b32_e32 v12, 0
	v_readfirstlane_b32 s50, v4
	s_mov_b32 m0, s50
	v_ashrrev_i32_e32 v4, 6, v6
	global_load_lds_dwordx4 v[2:3], off
	s_or_b32 s50, s21, s20
	v_lshrrev_b32_e32 v5, 30, v4
	s_ashr_i32 s51, s50, 31
	v_add_u32_e32 v5, v4, v5
	s_lshl_b64 s[50:51], s[50:51], 20
	v_bfe_u32 v2, v6, 4, 2
	v_bfe_u32 v3, v6, 1, 3
	v_and_b32_e32 v6, 0x7fffc, v5
	s_add_u32 s50, s34, s50
	v_sub_u32_e32 v4, v4, v6
	s_addc_u32 s51, s35, s51
	v_lshlrev_b32_e32 v137, 13, v4
	v_bitop3_b32 v4, v7, v3, 3 bitop3:0x6c
	v_bitop3_b32 v2, v2, v3, 4 bitop3:0x36
	v_lshl_add_u64 v[130:131], s[50:51], 0, v[0:1]
	s_add_u32 s50, s34, s49
	v_lshlrev_b32_e32 v5, 12, v5
	v_lshlrev_b32_e32 v4, 3, v4
	v_lshlrev_b32_e32 v2, 3, v2
	s_addc_u32 s51, s35, 0
	v_and_b32_e32 v136, 0xffffc000, v5
	v_lshl_add_u64 v[132:133], s[50:51], 0, v[0:1]
	s_mov_b64 s[50:51], 0
	v_lshlrev_b32_e32 v138, 1, v8
	v_lshlrev_b32_e32 v139, 1, v4
	v_lshlrev_b32_e32 v140, 1, v2
	s_mov_b32 s59, 0
	s_mov_b32 s49, 0
	v_mov_b32_e32 v13, v12
	v_mov_b32_e32 v14, v12
	v_mov_b32_e32 v15, v12
	v_mov_b32_e32 v24, v12
	v_mov_b32_e32 v25, v12
	v_mov_b32_e32 v26, v12
	v_mov_b32_e32 v27, v12
	v_mov_b32_e32 v0, v12
	v_mov_b32_e32 v1, v12
	v_mov_b32_e32 v2, v12
	v_mov_b32_e32 v3, v12
	v_mov_b32_e32 v4, v12
	v_mov_b32_e32 v5, v12
	v_mov_b32_e32 v6, v12
	v_mov_b32_e32 v7, v12
	v_mov_b32_e32 v8, v12
	v_mov_b32_e32 v9, v12
	v_mov_b32_e32 v10, v12
	v_mov_b32_e32 v11, v12
	v_mov_b32_e32 v16, v12
	v_mov_b32_e32 v17, v12
	v_mov_b32_e32 v18, v12
	v_mov_b32_e32 v19, v12
	v_mov_b32_e32 v20, v12
	v_mov_b32_e32 v21, v12
	v_mov_b32_e32 v22, v12
	v_mov_b32_e32 v23, v12
	v_mov_b32_e32 v28, v12
	v_mov_b32_e32 v29, v12
	v_mov_b32_e32 v30, v12
	v_mov_b32_e32 v31, v12
	v_mov_b32_e32 v32, v12
	v_mov_b32_e32 v33, v12
	v_mov_b32_e32 v34, v12
	v_mov_b32_e32 v35, v12
	v_mov_b32_e32 v36, v12
	v_mov_b32_e32 v37, v12
	v_mov_b32_e32 v38, v12
	v_mov_b32_e32 v39, v12
	v_mov_b32_e32 v40, v12
	v_mov_b32_e32 v41, v12
	v_mov_b32_e32 v42, v12
	v_mov_b32_e32 v43, v12
	v_mov_b32_e32 v44, v12
	v_mov_b32_e32 v45, v12
	v_mov_b32_e32 v46, v12
	v_mov_b32_e32 v47, v12
	v_mov_b32_e32 v48, v12
	v_mov_b32_e32 v49, v12
	v_mov_b32_e32 v50, v12
	v_mov_b32_e32 v51, v12
	v_mov_b32_e32 v52, v12
	v_mov_b32_e32 v53, v12
	v_mov_b32_e32 v54, v12
	v_mov_b32_e32 v55, v12
	v_mov_b32_e32 v56, v12
	v_mov_b32_e32 v57, v12
	v_mov_b32_e32 v58, v12
	v_mov_b32_e32 v59, v12
	v_mov_b32_e32 v60, v12
	v_mov_b32_e32 v61, v12
	v_mov_b32_e32 v62, v12
	v_mov_b32_e32 v63, v12
	v_mov_b32_e32 v64, v12
	v_mov_b32_e32 v65, v12
	v_mov_b32_e32 v66, v12
	v_mov_b32_e32 v67, v12
	v_mov_b32_e32 v68, v12
	v_mov_b32_e32 v69, v12
	v_mov_b32_e32 v70, v12
	v_mov_b32_e32 v71, v12
	v_mov_b32_e32 v72, v12
	v_mov_b32_e32 v73, v12
	v_mov_b32_e32 v74, v12
	v_mov_b32_e32 v75, v12
	v_mov_b32_e32 v76, v12
	v_mov_b32_e32 v77, v12
	v_mov_b32_e32 v78, v12
	v_mov_b32_e32 v79, v12
	v_mov_b32_e32 v80, v12
	v_mov_b32_e32 v81, v12
	v_mov_b32_e32 v82, v12
	v_mov_b32_e32 v83, v12
	v_mov_b32_e32 v84, v12
	v_mov_b32_e32 v85, v12
	v_mov_b32_e32 v86, v12
	v_mov_b32_e32 v87, v12
	v_mov_b32_e32 v88, v12
	v_mov_b32_e32 v89, v12
	v_mov_b32_e32 v90, v12
	v_mov_b32_e32 v91, v12
	v_mov_b32_e32 v92, v12
	v_mov_b32_e32 v93, v12
	v_mov_b32_e32 v94, v12
	v_mov_b32_e32 v95, v12
	v_mov_b32_e32 v96, v12
	v_mov_b32_e32 v97, v12
	v_mov_b32_e32 v98, v12
	v_mov_b32_e32 v99, v12
	v_mov_b32_e32 v100, v12
	v_mov_b32_e32 v101, v12
	v_mov_b32_e32 v102, v12
	v_mov_b32_e32 v103, v12
	v_mov_b32_e32 v104, v12
	v_mov_b32_e32 v105, v12
	v_mov_b32_e32 v106, v12
	v_mov_b32_e32 v107, v12
	v_mov_b32_e32 v108, v12
	v_mov_b32_e32 v109, v12
	v_mov_b32_e32 v110, v12
	v_mov_b32_e32 v111, v12
	v_mov_b32_e32 v112, v12
	v_mov_b32_e32 v113, v12
	v_mov_b32_e32 v114, v12
	v_mov_b32_e32 v115, v12
	v_mov_b32_e32 v116, v12
	v_mov_b32_e32 v117, v12
	v_mov_b32_e32 v118, v12
	v_mov_b32_e32 v119, v12
	v_mov_b32_e32 v120, v12
	v_mov_b32_e32 v121, v12
	v_mov_b32_e32 v122, v12
	v_mov_b32_e32 v123, v12
	v_mov_b32_e32 v124, v12
	v_mov_b32_e32 v125, v12
	v_mov_b32_e32 v126, v12
	v_mov_b32_e32 v127, v12
	s_waitcnt vmcnt(0) lgkmcnt(0)
	s_barrier
	s_nop 0
	v_add3_u32 v141, v136, v138, v139
	v_add3_u32 v210, v137, v138, v139
	v_add3_u32 v180, v136, v138, v140
	v_add3_u32 v211, v137, v138, v140
	v_xor_b32_e32 v212, 0x10000, v141
	v_xor_b32_e32 v213, 0x10000, v180
	v_xor_b32_e32 v214, 0x10000, v210
	v_xor_b32_e32 v215, 0x10000, v211
	v_readfirstlane_b32 s59, v135
	ds_read_b128 v[142:145], v141
	ds_read_b128 v[146:149], v141 offset:2048
	ds_read_b128 v[150:153], v141 offset:4096
	ds_read_b128 v[154:157], v141 offset:6144
	ds_read_b128 v[174:177], v210 offset:32768
	ds_read_b128 v[182:185], v210 offset:34816
	ds_read_b128 v[186:189], v210 offset:36864
	ds_read_b128 v[190:193], v210 offset:38912
	s_mov_b32 s49, 0
	s_mov_b64 s[50:51], s[34:35]
	v_subrev_u32_e32 v178, s34, v130
	v_subrev_u32_e32 v179, s34, v132
	s_add_u32 s59, s59, 0x10000
	s_mov_b32 m0, s59
	s_add_u32 s52, s50, s14
	s_addc_u32 s53, s51, s15
	global_load_lds_dwordx4 v178, s[52:53]
	s_add_u32 m0, s59, 0x2000
	s_add_u32 s52, s50, s16
	s_addc_u32 s53, s51, s17
	global_load_lds_dwordx4 v178, s[52:53]
	s_add_u32 m0, s59, 0x4000
	s_add_u32 s52, s50, s18
	s_addc_u32 s53, s51, s19
	global_load_lds_dwordx4 v178, s[52:53]
	s_add_u32 m0, s59, 0x6000
	s_add_u32 s52, s50, s22
	s_addc_u32 s53, s51, s23
	global_load_lds_dwordx4 v178, s[52:53]
	s_add_u32 m0, s59, 0x8000
	s_add_u32 s52, s50, s40
	s_addc_u32 s53, s51, s41
	global_load_lds_dwordx4 v179, s[52:53]
	s_add_u32 m0, s59, 0xa000
	s_add_u32 s52, s50, s42
	s_addc_u32 s53, s51, s43
	global_load_lds_dwordx4 v179, s[52:53]
	s_add_u32 m0, s59, 0xc000
	s_add_u32 s52, s50, s44
	s_addc_u32 s53, s51, s45
	global_load_lds_dwordx4 v179, s[52:53]
	s_add_u32 m0, s59, 0xe000
	s_add_u32 s52, s50, s46
	s_addc_u32 s53, s51, s47
	global_load_lds_dwordx4 v179, s[52:53]
	s_branch .Lg1_entry

.LBB0_452:
	s_ashr_i32 s46, s60, 3
	s_and_b32 s21, s60, 7
	s_and_b32 s62, s46, -8
	v_mov_b32_e32 v6, v181
	s_or_b32 s46, s62, s21
	s_ashr_i32 s47, s46, 31
	v_lshrrev_b32_e32 v7, 4, v6
	v_lshlrev_b32_e32 v1, 6, v6
	v_xor_b32_e32 v0, v7, v6
	v_and_b32_e32 v8, 0x3c0, v1
	v_lshlrev_b32_e32 v1, 7, v6
	s_and_b32 s20, s55, 7
	s_bfe_u32 s61, s60, 0x30003
	s_lshl_b64 s[48:49], s[46:47], 19
	v_lshlrev_b32_e32 v0, 3, v0
	v_and_b32_e32 v1, 0xfffffc00, v1
	s_add_u32 s48, s3, s48
	v_and_or_b32 v0, v0, 56, v1
	s_addc_u32 s49, s54, s49
	s_lshl_b32 s21, s61, 19
	v_ashrrev_i32_e32 v1, 31, v0
	v_lshl_add_u32 v140, v6, 4, 0
	s_add_u32 s50, s34, s21
	v_lshlrev_b64 v[0:1], 1, v[0:1]
	v_readfirstlane_b32 s21, v140
	v_add_u32_e32 v9, 0x2000, v140
	v_lshl_add_u64 v[2:3], s[48:49], 0, v[0:1]
	s_mov_b32 m0, s21
	v_readfirstlane_b32 s21, v9
	v_add_u32_e32 v9, 0x4000, v140
	s_barrier
	global_load_lds_dwordx4 v[2:3], off
	v_lshl_add_u64 v[4:5], v[2:3], 0, s[6:7]
	s_mov_b32 m0, s21
	v_readfirstlane_b32 s21, v9
	global_load_lds_dwordx4 v[4:5], off
	v_lshl_add_u64 v[4:5], v[2:3], 0, s[8:9]
	s_mov_b32 m0, s21
	v_lshl_add_u64 v[2:3], v[2:3], 0, s[10:11]
	global_load_lds_dwordx4 v[4:5], off
	v_add_u32_e32 v4, 0x6000, v140
	s_addc_u32 s51, s35, 0
	v_readfirstlane_b32 s21, v4
	s_mov_b32 m0, s21
	v_add_u32_e32 v4, 0xa000, v140
	global_load_lds_dwordx4 v[2:3], off
	v_add_u32_e32 v2, 0x8000, v140
	v_lshl_add_u64 v[132:133], s[50:51], 0, v[0:1]
	v_readfirstlane_b32 s21, v2
	s_mov_b32 m0, s21
	v_readfirstlane_b32 s21, v4
	v_add_u32_e32 v4, 0xc000, v140
	global_load_lds_dwordx4 v[132:133], off
	v_lshl_add_u64 v[2:3], v[132:133], 0, s[6:7]
	s_mov_b32 m0, s21
	v_readfirstlane_b32 s21, v4
	v_add_u32_e32 v4, 0xe000, v140
	global_load_lds_dwordx4 v[2:3], off
	v_lshl_add_u64 v[2:3], v[132:133], 0, s[8:9]
	s_mov_b32 m0, s21
	v_readfirstlane_b32 s21, v4
	global_load_lds_dwordx4 v[2:3], off
	v_lshl_add_u64 v[2:3], v[132:133], 0, s[10:11]
	s_mov_b32 m0, s21
	v_ashrrev_i32_e32 v4, 6, v6
	global_load_lds_dwordx4 v[2:3], off
	v_lshrrev_b32_e32 v5, 30, v4
	v_add_u32_e32 v5, v4, v5
	s_or_b32 s48, s62, s20
	v_bfe_u32 v2, v6, 4, 2
	v_bfe_u32 v3, v6, 1, 3
	v_and_b32_e32 v6, 0x7fffc, v5
	s_ashr_i32 s49, s48, 31
	v_sub_u32_e32 v4, v4, v6
	s_lshl_b64 s[48:49], s[48:49], 19
	v_lshlrev_b32_e32 v142, 13, v4
	v_bitop3_b32 v4, v7, v3, 3 bitop3:0x6c
	v_bitop3_b32 v2, v2, v3, 4 bitop3:0x36
	s_add_u32 s48, s34, s48
	v_lshlrev_b32_e32 v5, 12, v5
	v_lshlrev_b32_e32 v4, 3, v4
	v_lshlrev_b32_e32 v2, 3, v2
	s_addc_u32 s49, s35, s49
	v_and_b32_e32 v141, 0xffffc000, v5
	v_lshl_add_u64 v[134:135], s[48:49], 0, v[0:1]
	s_mov_b64 s[48:49], 0
	v_lshlrev_b32_e32 v143, 1, v8
	v_lshlrev_b32_e32 v144, 1, v4
	v_lshlrev_b32_e32 v145, 1, v2
	s_mov_b32 s62, 0
	s_mov_b32 s47, 0
	v_mov_b32_e32 v40, 0
	v_mov_b32_e32 v41, v129
	v_mov_b32_e32 v42, v129
	v_mov_b32_e32 v43, v129
	v_mov_b32_e32 v48, 0
	v_mov_b32_e32 v49, v129
	v_mov_b32_e32 v50, v129
	v_mov_b32_e32 v51, v129
	v_mov_b32_e32 v0, 0
	v_mov_b32_e32 v1, v129
	v_mov_b32_e32 v2, v129
	v_mov_b32_e32 v3, v129
	v_mov_b32_e32 v4, 0
	v_mov_b32_e32 v5, v129
	v_mov_b32_e32 v6, v129
	v_mov_b32_e32 v7, v129
	v_mov_b32_e32 v8, 0
	v_mov_b32_e32 v9, v129
	v_mov_b32_e32 v10, v129
	v_mov_b32_e32 v11, v129
	v_mov_b32_e32 v12, 0
	v_mov_b32_e32 v13, v129
	v_mov_b32_e32 v14, v129
	v_mov_b32_e32 v15, v129
	v_mov_b32_e32 v16, 0
	v_mov_b32_e32 v17, v129
	v_mov_b32_e32 v18, v129
	v_mov_b32_e32 v19, v129
	v_mov_b32_e32 v20, 0
	v_mov_b32_e32 v21, v129
	v_mov_b32_e32 v22, v129
	v_mov_b32_e32 v23, v129
	v_mov_b32_e32 v24, 0
	v_mov_b32_e32 v25, v129
	v_mov_b32_e32 v26, v129
	v_mov_b32_e32 v27, v129
	v_mov_b32_e32 v28, 0
	v_mov_b32_e32 v29, v129
	v_mov_b32_e32 v30, v129
	v_mov_b32_e32 v31, v129
	v_mov_b32_e32 v32, 0
	v_mov_b32_e32 v33, v129
	v_mov_b32_e32 v34, v129
	v_mov_b32_e32 v35, v129
	v_mov_b32_e32 v36, 0
	v_mov_b32_e32 v37, v129
	v_mov_b32_e32 v38, v129
	v_mov_b32_e32 v39, v129
	v_mov_b32_e32 v44, 0
	v_mov_b32_e32 v45, v129
	v_mov_b32_e32 v46, v129
	v_mov_b32_e32 v47, v129
	v_mov_b32_e32 v52, 0
	v_mov_b32_e32 v53, v129
	v_mov_b32_e32 v54, v129
	v_mov_b32_e32 v55, v129
	v_mov_b32_e32 v56, 0
	v_mov_b32_e32 v57, v129
	v_mov_b32_e32 v58, v129
	v_mov_b32_e32 v59, v129
	v_mov_b32_e32 v60, 0
	v_mov_b32_e32 v61, v129
	v_mov_b32_e32 v62, v129
	v_mov_b32_e32 v63, v129
	v_mov_b32_e32 v64, 0
	v_mov_b32_e32 v65, v129
	v_mov_b32_e32 v66, v129
	v_mov_b32_e32 v67, v129
	v_mov_b32_e32 v68, 0
	v_mov_b32_e32 v69, v129
	v_mov_b32_e32 v70, v129
	v_mov_b32_e32 v71, v129
	v_mov_b32_e32 v72, 0
	v_mov_b32_e32 v73, v129
	v_mov_b32_e32 v74, v129
	v_mov_b32_e32 v75, v129
	v_mov_b32_e32 v76, 0
	v_mov_b32_e32 v77, v129
	v_mov_b32_e32 v78, v129
	v_mov_b32_e32 v79, v129
	v_mov_b32_e32 v80, 0
	v_mov_b32_e32 v81, v129
	v_mov_b32_e32 v82, v129
	v_mov_b32_e32 v83, v129
	v_mov_b32_e32 v84, 0
	v_mov_b32_e32 v85, v129
	v_mov_b32_e32 v86, v129
	v_mov_b32_e32 v87, v129
	v_mov_b32_e32 v88, 0
	v_mov_b32_e32 v89, v129
	v_mov_b32_e32 v90, v129
	v_mov_b32_e32 v91, v129
	v_mov_b32_e32 v92, 0
	v_mov_b32_e32 v93, v129
	v_mov_b32_e32 v94, v129
	v_mov_b32_e32 v95, v129
	v_mov_b32_e32 v96, 0
	v_mov_b32_e32 v97, v129
	v_mov_b32_e32 v98, v129
	v_mov_b32_e32 v99, v129
	v_mov_b32_e32 v100, 0
	v_mov_b32_e32 v101, v129
	v_mov_b32_e32 v102, v129
	v_mov_b32_e32 v103, v129
	v_mov_b32_e32 v104, 0
	v_mov_b32_e32 v105, v129
	v_mov_b32_e32 v106, v129
	v_mov_b32_e32 v107, v129
	v_mov_b32_e32 v108, 0
	v_mov_b32_e32 v109, v129
	v_mov_b32_e32 v110, v129
	v_mov_b32_e32 v111, v129
	v_mov_b32_e32 v112, 0
	v_mov_b32_e32 v113, v129
	v_mov_b32_e32 v114, v129
	v_mov_b32_e32 v115, v129
	v_mov_b32_e32 v116, 0
	v_mov_b32_e32 v117, v129
	v_mov_b32_e32 v118, v129
	v_mov_b32_e32 v119, v129
	v_mov_b32_e32 v120, 0
	v_mov_b32_e32 v121, v129
	v_mov_b32_e32 v122, v129
	v_mov_b32_e32 v123, v129
	v_mov_b32_e32 v124, 0
	v_mov_b32_e32 v125, v129
	v_mov_b32_e32 v126, v129
	v_mov_b32_e32 v127, v129
	s_waitcnt vmcnt(0) lgkmcnt(0)
	s_barrier
	s_nop 0
	v_add3_u32 v180, v141, v143, v144
	v_add3_u32 v215, v142, v143, v144
	v_add3_u32 v214, v141, v143, v145
	v_add3_u32 v216, v142, v143, v145
	v_xor_b32_e32 v217, 0x10000, v180
	v_xor_b32_e32 v218, 0x10000, v214
	v_xor_b32_e32 v219, 0x10000, v215
	v_xor_b32_e32 v220, 0x10000, v216
	v_readfirstlane_b32 s62, v140
	ds_read_b128 v[146:149], v180
	ds_read_b128 v[150:153], v180 offset:2048
	ds_read_b128 v[154:157], v180 offset:4096
	ds_read_b128 v[158:161], v180 offset:6144
	ds_read_b128 v[182:185], v215 offset:32768
	ds_read_b128 v[186:189], v215 offset:34816
	ds_read_b128 v[190:193], v215 offset:36864
	ds_read_b128 v[194:197], v215 offset:38912
	s_mov_b32 s47, 0
	s_mov_b64 s[48:49], s[34:35]
	v_subrev_u32_e32 v178, s34, v134
	v_subrev_u32_e32 v179, s34, v132
	s_add_u32 s62, s62, 0x10000
	s_mov_b32 m0, s62
	s_add_u32 s50, s48, s12
	s_addc_u32 s51, s49, s13
	global_load_lds_dwordx4 v178, s[50:51]
	s_add_u32 m0, s62, 0x2000
	s_add_u32 s50, s48, s14
	s_addc_u32 s51, s49, s15
	global_load_lds_dwordx4 v178, s[50:51]
	s_add_u32 m0, s62, 0x4000
	s_add_u32 s50, s48, s16
	s_addc_u32 s51, s49, s17
	global_load_lds_dwordx4 v178, s[50:51]
	s_add_u32 m0, s62, 0x6000
	s_add_u32 s50, s48, s18
	s_addc_u32 s51, s49, s19
	global_load_lds_dwordx4 v178, s[50:51]
	s_add_u32 m0, s62, 0x8000
	s_add_u32 s50, s48, s22
	s_addc_u32 s51, s49, s23
	global_load_lds_dwordx4 v179, s[50:51]
	s_add_u32 m0, s62, 0xa000
	s_add_u32 s50, s48, s36
	s_addc_u32 s51, s49, s37
	global_load_lds_dwordx4 v179, s[50:51]
	s_add_u32 m0, s62, 0xc000
	s_add_u32 s50, s48, s40
	s_addc_u32 s51, s49, s41
	global_load_lds_dwordx4 v179, s[50:51]
	s_add_u32 m0, s62, 0xe000
	s_add_u32 s50, s48, s42
	s_addc_u32 s51, s49, s43
	global_load_lds_dwordx4 v179, s[50:51]
	s_branch .Lg2_entry

.LBB0_667:
	ds_read_b128 v[2:5], v0
	v_lshl_add_u64 v[6:7], v[138:139], 0, s[68:69]
	v_add_co_u32_e32 v8, vcc, 0x6000000, v6
	s_add_u32 s68, s68, 0x20000
	s_nop 0
	v_addc_co_u32_e32 v9, vcc, 0, v7, vcc
	s_waitcnt lgkmcnt(0)
	global_store_dwordx4 v[8:9], v[2:5], off sc1
	ds_read_b128 v[2:5], v0 offset:1152
	v_add_co_u32_e32 v8, vcc, 0x6008000, v6
	s_addc_u32 s69, s69, 0
	s_nop 0
	v_addc_co_u32_e32 v9, vcc, 0, v7, vcc
	s_waitcnt lgkmcnt(0)
	global_store_dwordx4 v[8:9], v[2:5], off sc1
	ds_read_b128 v[2:5], v0 offset:2304
	v_add_co_u32_e32 v8, vcc, 0x6010000, v6
	s_cmp_lg_u32 s68, 0x80000
	s_nop 0
	v_addc_co_u32_e32 v9, vcc, 0, v7, vcc
	s_waitcnt lgkmcnt(0)
	global_store_dwordx4 v[8:9], v[2:5], off sc1
	ds_read_b128 v[2:5], v0 offset:3456
	v_add_co_u32_e32 v6, vcc, 0x6018000, v6
	v_add_u32_e32 v0, 0x1200, v0
	s_nop 0
	v_addc_co_u32_e32 v7, vcc, 0, v7, vcc
	s_waitcnt lgkmcnt(0)
	global_store_dwordx4 v[6:7], v[2:5], off sc1
	s_cbranch_scc1 .LBB0_667
	v_mov_b32_e32 v6, v181
	s_waitcnt lgkmcnt(0)
	s_lshl_b32 s68, s6, 20
	v_lshrrev_b32_e32 v7, 4, v6
	v_lshlrev_b32_e32 v1, 6, v6
	v_xor_b32_e32 v0, v7, v6
	v_and_b32_e32 v8, 0x3c0, v1
	v_lshlrev_b32_e32 v1, 8, v6
	v_lshlrev_b32_e32 v0, 3, v0
	v_and_b32_e32 v1, 0xfffff800, v1
	s_lshl_b64 s[20:21], s[64:65], 20
	v_and_or_b32 v0, v0, 56, v1
	s_add_u32 s20, s75, s20
	v_ashrrev_i32_e32 v1, 31, v0
	s_addc_u32 s21, s88, s21
	v_lshlrev_b64 v[0:1], 1, v[0:1]
	v_lshl_add_u32 v174, v6, 4, 0
	v_lshl_add_u64 v[2:3], s[20:21], 0, v[0:1]
	v_readfirstlane_b32 s20, v174
	v_add_u32_e32 v9, 0x2000, v174
	s_mov_b32 m0, s20
	v_readfirstlane_b32 s20, v9
	v_add_u32_e32 v9, 0x4000, v174
	s_barrier
	global_load_lds_dwordx4 v[2:3], off
	v_lshl_add_u64 v[4:5], v[2:3], 0, s[10:11]
	s_mov_b32 m0, s20
	v_readfirstlane_b32 s20, v9
	global_load_lds_dwordx4 v[4:5], off
	v_lshl_add_u64 v[4:5], v[2:3], 0, s[40:41]
	s_mov_b32 m0, s20
	s_lshl_b32 s64, s95, 12
	global_load_lds_dwordx4 v[4:5], off
	v_add_u32_e32 v4, 0x6000, v174
	s_add_u32 s64, s89, s64
	v_readfirstlane_b32 s20, v4
	v_add_u32_e32 v4, 0x8000, v174
	s_addc_u32 s65, s90, 0
	v_lshl_add_u64 v[2:3], v[2:3], 0, s[42:43]
	s_mov_b32 m0, s20
	v_readfirstlane_b32 s20, v4
	v_add_u32_e32 v9, 0xa000, v174
	global_load_lds_dwordx4 v[2:3], off
	v_lshl_add_u64 v[2:3], s[64:65], 0, v[0:1]
	s_mov_b32 m0, s20
	v_readfirstlane_b32 s20, v9
	v_add_u32_e32 v9, 0xc000, v174
	global_load_lds_dwordx4 v[2:3], off
	v_lshl_add_u64 v[4:5], v[2:3], 0, s[10:11]
	s_mov_b32 m0, s20
	v_readfirstlane_b32 s20, v9
	global_load_lds_dwordx4 v[4:5], off
	v_lshl_add_u64 v[4:5], v[2:3], 0, s[40:41]
	s_mov_b32 m0, s20
	v_lshl_add_u64 v[2:3], v[2:3], 0, s[42:43]
	global_load_lds_dwordx4 v[4:5], off
	v_add_u32_e32 v4, 0xe000, v174
	s_mov_b32 s69, 0
	v_readfirstlane_b32 s20, v4
	s_mov_b32 m0, s20
	v_ashrrev_i32_e32 v4, 6, v6
	global_load_lds_dwordx4 v[2:3], off
	v_lshrrev_b32_e32 v5, 30, v4
	v_add_u32_e32 v5, v4, v5
	s_lshl_b64 s[20:21], s[66:67], 20
	v_bfe_u32 v2, v6, 4, 2
	v_bfe_u32 v3, v6, 1, 3
	v_and_b32_e32 v6, 0x7fffc, v5
	s_add_u32 s20, s34, s20
	v_sub_u32_e32 v4, v4, v6
	s_addc_u32 s21, s35, s21
	v_lshlrev_b32_e32 v5, 12, v5
	v_lshlrev_b32_e32 v176, 13, v4
	v_bitop3_b32 v4, v7, v3, 3 bitop3:0x6c
	v_bitop3_b32 v2, v2, v3, 4 bitop3:0x36
	v_lshl_add_u64 v[142:143], s[20:21], 0, v[0:1]
	s_add_u32 s20, s34, s68
	v_and_b32_e32 v175, 0xffffc000, v5
	v_lshlrev_b32_e32 v5, 3, v4
	v_lshlrev_b32_e32 v2, 3, v2
	s_addc_u32 s21, s35, 0
	v_mov_b32_e32 v4, 0
	v_lshl_add_u64 v[144:145], s[20:21], 0, v[0:1]
	s_mov_b64 s[64:65], 0
	v_lshlrev_b32_e32 v177, 1, v8
	v_lshlrev_b32_e32 v178, 1, v5
	v_lshlrev_b32_e32 v179, 1, v2
	s_mov_b32 s68, 0
	v_mov_b32_e32 v5, v4
	v_mov_b32_e32 v6, v4
	v_mov_b32_e32 v7, v4
	v_mov_b32_e32 v8, v4
	v_mov_b32_e32 v9, v4
	v_mov_b32_e32 v10, v4
	v_mov_b32_e32 v11, v4
	v_mov_b32_e32 v0, v4
	v_mov_b32_e32 v1, v4
	v_mov_b32_e32 v2, v4
	v_mov_b32_e32 v3, v4
	v_mov_b32_e32 v12, v4
	v_mov_b32_e32 v13, v4
	v_mov_b32_e32 v14, v4
	v_mov_b32_e32 v15, v4
	v_mov_b32_e32 v16, v4
	v_mov_b32_e32 v17, v4
	v_mov_b32_e32 v18, v4
	v_mov_b32_e32 v19, v4
	v_mov_b32_e32 v20, v4
	v_mov_b32_e32 v21, v4
	v_mov_b32_e32 v22, v4
	v_mov_b32_e32 v23, v4
	v_mov_b32_e32 v24, v4
	v_mov_b32_e32 v25, v4
	v_mov_b32_e32 v26, v4
	v_mov_b32_e32 v27, v4
	v_mov_b32_e32 v28, v4
	v_mov_b32_e32 v29, v4
	v_mov_b32_e32 v30, v4
	v_mov_b32_e32 v31, v4
	v_mov_b32_e32 v32, v4
	v_mov_b32_e32 v33, v4
	v_mov_b32_e32 v34, v4
	v_mov_b32_e32 v35, v4
	v_mov_b32_e32 v36, v4
	v_mov_b32_e32 v37, v4
	v_mov_b32_e32 v38, v4
	v_mov_b32_e32 v39, v4
	v_mov_b32_e32 v40, v4
	v_mov_b32_e32 v41, v4
	v_mov_b32_e32 v42, v4
	v_mov_b32_e32 v43, v4
	v_mov_b32_e32 v44, v4
	v_mov_b32_e32 v45, v4
	v_mov_b32_e32 v46, v4
	v_mov_b32_e32 v47, v4
	v_mov_b32_e32 v48, v4
	v_mov_b32_e32 v49, v4
	v_mov_b32_e32 v50, v4
	v_mov_b32_e32 v51, v4
	v_mov_b32_e32 v52, v4
	v_mov_b32_e32 v53, v4
	v_mov_b32_e32 v54, v4
	v_mov_b32_e32 v55, v4
	v_mov_b32_e32 v56, v4
	v_mov_b32_e32 v57, v4
	v_mov_b32_e32 v58, v4
	v_mov_b32_e32 v59, v4
	v_mov_b32_e32 v60, v4
	v_mov_b32_e32 v61, v4
	v_mov_b32_e32 v62, v4
	v_mov_b32_e32 v63, v4
	v_mov_b32_e32 v64, v4
	v_mov_b32_e32 v65, v4
	v_mov_b32_e32 v66, v4
	v_mov_b32_e32 v67, v4
	v_mov_b32_e32 v68, v4
	v_mov_b32_e32 v69, v4
	v_mov_b32_e32 v70, v4
	v_mov_b32_e32 v71, v4
	v_mov_b32_e32 v72, v4
	v_mov_b32_e32 v73, v4
	v_mov_b32_e32 v74, v4
	v_mov_b32_e32 v75, v4
	v_mov_b32_e32 v76, v4
	v_mov_b32_e32 v77, v4
	v_mov_b32_e32 v78, v4
	v_mov_b32_e32 v79, v4
	v_mov_b32_e32 v80, v4
	v_mov_b32_e32 v81, v4
	v_mov_b32_e32 v82, v4
	v_mov_b32_e32 v83, v4
	v_mov_b32_e32 v84, v4
	v_mov_b32_e32 v85, v4
	v_mov_b32_e32 v86, v4
	v_mov_b32_e32 v87, v4
	v_mov_b32_e32 v88, v4
	v_mov_b32_e32 v89, v4
	v_mov_b32_e32 v90, v4
	v_mov_b32_e32 v91, v4
	v_mov_b32_e32 v92, v4
	v_mov_b32_e32 v93, v4
	v_mov_b32_e32 v94, v4
	v_mov_b32_e32 v95, v4
	v_mov_b32_e32 v96, v4
	v_mov_b32_e32 v97, v4
	v_mov_b32_e32 v98, v4
	v_mov_b32_e32 v99, v4
	v_mov_b32_e32 v100, v4
	v_mov_b32_e32 v101, v4
	v_mov_b32_e32 v102, v4
	v_mov_b32_e32 v103, v4
	v_mov_b32_e32 v104, v4
	v_mov_b32_e32 v105, v4
	v_mov_b32_e32 v106, v4
	v_mov_b32_e32 v107, v4
	v_mov_b32_e32 v108, v4
	v_mov_b32_e32 v109, v4
	v_mov_b32_e32 v110, v4
	v_mov_b32_e32 v111, v4
	v_mov_b32_e32 v112, v4
	v_mov_b32_e32 v113, v4
	v_mov_b32_e32 v114, v4
	v_mov_b32_e32 v115, v4
	v_mov_b32_e32 v116, v4
	v_mov_b32_e32 v117, v4
	v_mov_b32_e32 v118, v4
	v_mov_b32_e32 v119, v4
	v_mov_b32_e32 v120, v4
	v_mov_b32_e32 v121, v4
	v_mov_b32_e32 v122, v4
	v_mov_b32_e32 v123, v4
	v_mov_b32_e32 v124, v4
	v_mov_b32_e32 v125, v4
	v_mov_b32_e32 v126, v4
	v_mov_b32_e32 v127, v4
	s_waitcnt vmcnt(0) lgkmcnt(0)
	s_barrier
	s_nop 0
	v_add3_u32 v180, v175, v177, v178
	v_add3_u32 v249, v176, v177, v178
	v_add3_u32 v248, v175, v177, v179
	v_add3_u32 v250, v176, v177, v179
	v_readfirstlane_b32 s69, v174
	ds_read_b128 v[182:185], v180
	ds_read_b128 v[186:189], v180 offset:2048
	ds_read_b128 v[190:193], v180 offset:4096
	ds_read_b128 v[194:197], v180 offset:6144
	ds_read_b128 v[214:217], v249 offset:32768
	ds_read_b128 v[218:221], v249 offset:34816
	ds_read_b128 v[222:225], v249 offset:36864
	ds_read_b128 v[226:229], v249 offset:38912
	s_mov_b32 s68, 0
	s_mov_b64 s[64:65], s[34:35]
	v_subrev_u32_e32 v246, s34, v142
	v_subrev_u32_e32 v247, s34, v144
	s_add_u32 s69, s69, 0x10000
	s_mov_b32 m0, s69
	s_add_u32 s66, s64, s44
	s_addc_u32 s67, s65, s45
	global_load_lds_dwordx4 v246, s[66:67]
	s_add_u32 m0, s69, 0x2000
	s_add_u32 s66, s64, s46
	s_addc_u32 s67, s65, s47
	global_load_lds_dwordx4 v246, s[66:67]
	s_add_u32 m0, s69, 0x4000
	s_add_u32 s66, s64, s48
	s_addc_u32 s67, s65, s49
	global_load_lds_dwordx4 v246, s[66:67]
	s_add_u32 m0, s69, 0x6000
	s_add_u32 s66, s64, s50
	s_addc_u32 s67, s65, s51
	global_load_lds_dwordx4 v246, s[66:67]
	s_add_u32 m0, s69, 0x8000
	s_add_u32 s66, s64, s52
	s_addc_u32 s67, s65, s53
	global_load_lds_dwordx4 v247, s[66:67]
	s_add_u32 m0, s69, 0xa000
	s_add_u32 s66, s64, s54
	s_addc_u32 s67, s65, s55
	global_load_lds_dwordx4 v247, s[66:67]
	s_add_u32 m0, s69, 0xc000
	s_add_u32 s66, s64, s60
	s_addc_u32 s67, s65, s61
	global_load_lds_dwordx4 v247, s[66:67]
	s_add_u32 m0, s69, 0xe000
	s_add_u32 s66, s64, s62
	s_addc_u32 s67, s65, s63
	global_load_lds_dwordx4 v247, s[66:67]
	s_branch .Lg6_entry

.LBB0_746:
	s_ashr_i32 s20, s60, 2
	v_mov_b32_e32 v6, v181
	s_and_b32 s6, s60, 7
	s_and_b32 s51, s20, -8
	s_or_b32 s46, s51, s6
	v_lshrrev_b32_e32 v7, 4, v6
	v_lshlrev_b32_e32 v1, 6, v6
	v_xor_b32_e32 v0, v7, v6
	v_and_b32_e32 v8, 0x3c0, v1
	v_lshlrev_b32_e32 v1, 8, v6
	s_ashr_i32 s47, s46, 31
	v_lshlrev_b32_e32 v0, 3, v0
	v_and_b32_e32 v1, 0xfffff800, v1
	s_and_b32 s50, s55, 7
	s_bfe_u32 s6, s60, 0x20003
	s_lshl_b64 s[20:21], s[46:47], 20
	v_and_or_b32 v0, v0, 56, v1
	s_add_u32 s20, s3, s20
	v_ashrrev_i32_e32 v1, 31, v0
	s_addc_u32 s21, s52, s21
	v_lshlrev_b64 v[0:1], 1, v[0:1]
	v_lshl_add_u32 v134, v6, 4, 0
	v_lshl_add_u64 v[2:3], s[20:21], 0, v[0:1]
	v_readfirstlane_b32 s20, v134
	v_add_u32_e32 v9, 0x2000, v134
	s_mov_b32 m0, s20
	v_readfirstlane_b32 s20, v9
	v_add_u32_e32 v9, 0x4000, v134
	s_waitcnt vmcnt(63) expcnt(7) lgkmcnt(15)
	s_barrier
	global_load_lds_dwordx4 v[2:3], off
	v_lshl_add_u64 v[4:5], v[2:3], 0, s[8:9]
	s_mov_b32 m0, s20
	v_readfirstlane_b32 s20, v9
	global_load_lds_dwordx4 v[4:5], off
	v_lshl_add_u64 v[4:5], v[2:3], 0, s[10:11]
	s_mov_b32 m0, s20
	s_lshl_b32 s47, s6, 20
	global_load_lds_dwordx4 v[4:5], off
	v_add_u32_e32 v4, 0x6000, v134
	s_add_u32 s48, s53, s47
	v_readfirstlane_b32 s20, v4
	v_add_u32_e32 v4, 0x8000, v134
	s_addc_u32 s49, s54, 0
	v_lshl_add_u64 v[2:3], v[2:3], 0, s[12:13]
	s_mov_b32 m0, s20
	v_readfirstlane_b32 s20, v4
	v_add_u32_e32 v9, 0xa000, v134
	global_load_lds_dwordx4 v[2:3], off
	v_lshl_add_u64 v[2:3], s[48:49], 0, v[0:1]
	s_mov_b32 m0, s20
	v_readfirstlane_b32 s20, v9
	v_add_u32_e32 v9, 0xc000, v134
	global_load_lds_dwordx4 v[2:3], off
	v_lshl_add_u64 v[4:5], v[2:3], 0, s[8:9]
	s_mov_b32 m0, s20
	v_readfirstlane_b32 s20, v9
	global_load_lds_dwordx4 v[4:5], off
	v_lshl_add_u64 v[4:5], v[2:3], 0, s[10:11]
	s_mov_b32 m0, s20
	v_lshl_add_u64 v[2:3], v[2:3], 0, s[12:13]
	global_load_lds_dwordx4 v[4:5], off
	v_add_u32_e32 v4, 0xe000, v134
	v_mov_b32_e32 v36, 0
	v_readfirstlane_b32 s20, v4
	s_mov_b32 m0, s20
	v_ashrrev_i32_e32 v4, 6, v6
	global_load_lds_dwordx4 v[2:3], off
	s_or_b32 s20, s51, s50
	v_lshrrev_b32_e32 v5, 30, v4
	s_ashr_i32 s21, s20, 31
	v_add_u32_e32 v5, v4, v5
	s_lshl_b64 s[20:21], s[20:21], 20
	v_bfe_u32 v2, v6, 4, 2
	v_bfe_u32 v3, v6, 1, 3
	v_and_b32_e32 v6, 0x7fffc, v5
	s_add_u32 s20, s34, s20
	v_sub_u32_e32 v4, v4, v6
	s_addc_u32 s21, s35, s21
	v_lshlrev_b32_e32 v136, 13, v4
	v_bitop3_b32 v4, v7, v3, 3 bitop3:0x6c
	v_bitop3_b32 v2, v2, v3, 4 bitop3:0x36
	v_lshl_add_u64 v[130:131], s[20:21], 0, v[0:1]
	s_add_u32 s20, s34, s47
	v_lshlrev_b32_e32 v5, 12, v5
	v_lshlrev_b32_e32 v4, 3, v4
	v_lshlrev_b32_e32 v2, 3, v2
	s_addc_u32 s21, s35, 0
	v_and_b32_e32 v135, 0xffffc000, v5
	v_lshl_add_u64 v[132:133], s[20:21], 0, v[0:1]
	s_mov_b64 s[48:49], 0
	v_lshlrev_b32_e32 v137, 1, v8
	v_lshlrev_b32_e32 v138, 1, v4
	v_lshlrev_b32_e32 v139, 1, v2
	s_mov_b32 s61, 0
	s_mov_b32 s47, 0
	v_mov_b32_e32 v37, v36
	v_mov_b32_e32 v38, v36
	v_mov_b32_e32 v39, v36
	v_mov_b32_e32 v40, v36
	v_mov_b32_e32 v41, v36
	v_mov_b32_e32 v42, v36
	v_mov_b32_e32 v43, v36
	v_mov_b32_e32 v0, v36
	v_mov_b32_e32 v1, v36
	v_mov_b32_e32 v2, v36
	v_mov_b32_e32 v3, v36
	v_mov_b32_e32 v4, v36
	v_mov_b32_e32 v5, v36
	v_mov_b32_e32 v6, v36
	v_mov_b32_e32 v7, v36
	v_mov_b32_e32 v8, v36
	v_mov_b32_e32 v9, v36
	v_mov_b32_e32 v10, v36
	v_mov_b32_e32 v11, v36
	v_mov_b32_e32 v12, v36
	v_mov_b32_e32 v13, v36
	v_mov_b32_e32 v14, v36
	v_mov_b32_e32 v15, v36
	v_mov_b32_e32 v16, v36
	v_mov_b32_e32 v17, v36
	v_mov_b32_e32 v18, v36
	v_mov_b32_e32 v19, v36
	v_mov_b32_e32 v20, v36
	v_mov_b32_e32 v21, v36
	v_mov_b32_e32 v22, v36
	v_mov_b32_e32 v23, v36
	v_mov_b32_e32 v24, v36
	v_mov_b32_e32 v25, v36
	v_mov_b32_e32 v26, v36
	v_mov_b32_e32 v27, v36
	v_mov_b32_e32 v28, v36
	v_mov_b32_e32 v29, v36
	v_mov_b32_e32 v30, v36
	v_mov_b32_e32 v31, v36
	v_mov_b32_e32 v32, v36
	v_mov_b32_e32 v33, v36
	v_mov_b32_e32 v34, v36
	v_mov_b32_e32 v35, v36
	v_mov_b32_e32 v44, v36
	v_mov_b32_e32 v45, v36
	v_mov_b32_e32 v46, v36
	v_mov_b32_e32 v47, v36
	v_mov_b32_e32 v48, v36
	v_mov_b32_e32 v49, v36
	v_mov_b32_e32 v50, v36
	v_mov_b32_e32 v51, v36
	v_mov_b32_e32 v52, v36
	v_mov_b32_e32 v53, v36
	v_mov_b32_e32 v54, v36
	v_mov_b32_e32 v55, v36
	v_mov_b32_e32 v56, v36
	v_mov_b32_e32 v57, v36
	v_mov_b32_e32 v58, v36
	v_mov_b32_e32 v59, v36
	v_mov_b32_e32 v60, v36
	v_mov_b32_e32 v61, v36
	v_mov_b32_e32 v62, v36
	v_mov_b32_e32 v63, v36
	v_mov_b32_e32 v64, v36
	v_mov_b32_e32 v65, v36
	v_mov_b32_e32 v66, v36
	v_mov_b32_e32 v67, v36
	v_mov_b32_e32 v68, v36
	v_mov_b32_e32 v69, v36
	v_mov_b32_e32 v70, v36
	v_mov_b32_e32 v71, v36
	v_mov_b32_e32 v72, v36
	v_mov_b32_e32 v73, v36
	v_mov_b32_e32 v74, v36
	v_mov_b32_e32 v75, v36
	v_mov_b32_e32 v76, v36
	v_mov_b32_e32 v77, v36
	v_mov_b32_e32 v78, v36
	v_mov_b32_e32 v79, v36
	v_mov_b32_e32 v80, v36
	v_mov_b32_e32 v81, v36
	v_mov_b32_e32 v82, v36
	v_mov_b32_e32 v83, v36
	v_mov_b32_e32 v84, v36
	v_mov_b32_e32 v85, v36
	v_mov_b32_e32 v86, v36
	v_mov_b32_e32 v87, v36
	v_mov_b32_e32 v88, v36
	v_mov_b32_e32 v89, v36
	v_mov_b32_e32 v90, v36
	v_mov_b32_e32 v91, v36
	v_mov_b32_e32 v92, v36
	v_mov_b32_e32 v93, v36
	v_mov_b32_e32 v94, v36
	v_mov_b32_e32 v95, v36
	v_mov_b32_e32 v96, v36
	v_mov_b32_e32 v97, v36
	v_mov_b32_e32 v98, v36
	v_mov_b32_e32 v99, v36
	v_mov_b32_e32 v100, v36
	v_mov_b32_e32 v101, v36
	v_mov_b32_e32 v102, v36
	v_mov_b32_e32 v103, v36
	v_mov_b32_e32 v104, v36
	v_mov_b32_e32 v105, v36
	v_mov_b32_e32 v106, v36
	v_mov_b32_e32 v107, v36
	v_mov_b32_e32 v108, v36
	v_mov_b32_e32 v109, v36
	v_mov_b32_e32 v110, v36
	v_mov_b32_e32 v111, v36
	v_mov_b32_e32 v112, v36
	v_mov_b32_e32 v113, v36
	v_mov_b32_e32 v114, v36
	v_mov_b32_e32 v115, v36
	v_mov_b32_e32 v116, v36
	v_mov_b32_e32 v117, v36
	v_mov_b32_e32 v118, v36
	v_mov_b32_e32 v119, v36
	v_mov_b32_e32 v120, v36
	v_mov_b32_e32 v121, v36
	v_mov_b32_e32 v122, v36
	v_mov_b32_e32 v123, v36
	v_mov_b32_e32 v124, v36
	v_mov_b32_e32 v125, v36
	v_mov_b32_e32 v126, v36
	v_mov_b32_e32 v127, v36
	s_waitcnt vmcnt(0) lgkmcnt(0)
	s_barrier
	s_nop 0
	v_add3_u32 v141, v135, v137, v138
	v_add3_u32 v210, v136, v137, v138
	v_add3_u32 v180, v135, v137, v139
	v_add3_u32 v211, v136, v137, v139
	v_xor_b32_e32 v212, 0x10000, v141
	v_xor_b32_e32 v213, 0x10000, v180
	v_xor_b32_e32 v214, 0x10000, v210
	v_xor_b32_e32 v215, 0x10000, v211
	v_readfirstlane_b32 s61, v134
	ds_read_b128 v[142:145], v141
	ds_read_b128 v[146:149], v141 offset:2048
	ds_read_b128 v[150:153], v141 offset:4096
	ds_read_b128 v[154:157], v141 offset:6144
	ds_read_b128 v[174:177], v210 offset:32768
	ds_read_b128 v[182:185], v210 offset:34816
	ds_read_b128 v[186:189], v210 offset:36864
	ds_read_b128 v[190:193], v210 offset:38912
	s_mov_b32 s47, 0
	s_mov_b64 s[48:49], s[34:35]
	v_subrev_u32_e32 v178, s34, v130
	v_subrev_u32_e32 v179, s34, v132
	s_add_u32 s61, s61, 0x10000
	s_mov_b32 m0, s61
	s_add_u32 s50, s48, s14
	s_addc_u32 s51, s49, s15
	global_load_lds_dwordx4 v178, s[50:51]
	s_add_u32 m0, s61, 0x2000
	s_add_u32 s50, s48, s16
	s_addc_u32 s51, s49, s17
	global_load_lds_dwordx4 v178, s[50:51]
	s_add_u32 m0, s61, 0x4000
	s_add_u32 s50, s48, s18
	s_addc_u32 s51, s49, s19
	global_load_lds_dwordx4 v178, s[50:51]
	s_add_u32 m0, s61, 0x6000
	s_add_u32 s50, s48, s22
	s_addc_u32 s51, s49, s23
	global_load_lds_dwordx4 v178, s[50:51]
	s_add_u32 m0, s61, 0x8000
	s_add_u32 s50, s48, s36
	s_addc_u32 s51, s49, s37
	global_load_lds_dwordx4 v179, s[50:51]
	s_add_u32 m0, s61, 0xa000
	s_add_u32 s50, s48, s40
	s_addc_u32 s51, s49, s41
	global_load_lds_dwordx4 v179, s[50:51]
	s_add_u32 m0, s61, 0xc000
	s_add_u32 s50, s48, s42
	s_addc_u32 s51, s49, s43
	global_load_lds_dwordx4 v179, s[50:51]
	s_add_u32 m0, s61, 0xe000
	s_add_u32 s50, s48, s44
	s_addc_u32 s51, s49, s45
	global_load_lds_dwordx4 v179, s[50:51]
	s_branch .Lg7_entry

.LBB0_933:
	s_mul_hi_i32 s21, s70, 0x2e8ba2e9
	s_lshr_b32 s56, s21, 31
	s_ashr_i32 s71, s21, 4
	s_add_i32 s71, s71, s56
	s_and_b32 s20, s70, 7
	s_lshl_b32 s62, s71, 3
	s_or_b32 s58, s62, s20
	s_ashr_i32 s20, s70, 3
	s_mul_hi_i32 s21, s20, 0x2e8ba2e9
	v_mov_b32_e32 v6, v181
	s_lshr_b32 s56, s21, 31
	s_ashr_i32 s21, s21, 1
	s_add_i32 s21, s21, s56
	v_lshrrev_b32_e32 v7, 4, v6
	v_lshlrev_b32_e32 v1, 6, v6
	v_xor_b32_e32 v0, v7, v6
	v_and_b32_e32 v8, 0x3c0, v1
	v_lshlrev_b32_e32 v1, 7, v6
	s_mul_i32 s21, s21, 11
	s_ashr_i32 s59, s58, 31
	v_lshlrev_b32_e32 v0, 3, v0
	v_and_b32_e32 v1, 0xfffffc00, v1
	s_and_b32 s64, s69, 7
	s_sub_i32 s56, s20, s21
	s_lshl_b64 s[20:21], s[58:59], 19
	v_and_or_b32 v0, v0, 56, v1
	s_add_u32 s20, s3, s20
	v_ashrrev_i32_e32 v1, 31, v0
	s_addc_u32 s21, s66, s21
	v_lshlrev_b64 v[0:1], 1, v[0:1]
	v_lshl_add_u32 v130, v6, 4, 0
	v_lshl_add_u64 v[2:3], s[20:21], 0, v[0:1]
	v_readfirstlane_b32 s20, v130
	v_add_u32_e32 v9, 0x2000, v130
	s_mov_b32 m0, s20
	v_readfirstlane_b32 s20, v9
	v_add_u32_e32 v9, 0x4000, v130
	s_waitcnt vmcnt(63) expcnt(7) lgkmcnt(15)
	s_barrier
	global_load_lds_dwordx4 v[2:3], off
	v_lshl_add_u64 v[4:5], v[2:3], 0, s[14:15]
	s_mov_b32 m0, s20
	v_readfirstlane_b32 s20, v9
	global_load_lds_dwordx4 v[4:5], off
	v_lshl_add_u64 v[4:5], v[2:3], 0, s[16:17]
	s_mov_b32 m0, s20
	s_ashr_i32 s57, s56, 31
	global_load_lds_dwordx4 v[4:5], off
	v_add_u32_e32 v4, 0x6000, v130
	s_lshl_b64 s[60:61], s[56:57], 19
	v_readfirstlane_b32 s20, v4
	v_lshl_add_u64 v[2:3], v[2:3], 0, s[18:19]
	s_mov_b32 m0, s20
	s_add_u32 s60, s34, s60
	global_load_lds_dwordx4 v[2:3], off
	v_add_u32_e32 v2, 0x8000, v130
	s_addc_u32 s61, s35, s61
	v_readfirstlane_b32 s20, v2
	v_add_u32_e32 v4, 0xa000, v130
	v_lshl_add_u64 v[140:141], s[60:61], 0, v[0:1]
	s_mov_b32 m0, s20
	v_readfirstlane_b32 s20, v4
	v_add_u32_e32 v4, 0xc000, v130
	global_load_lds_dwordx4 v[140:141], off
	v_lshl_add_u64 v[2:3], v[140:141], 0, s[14:15]
	s_mov_b32 m0, s20
	v_readfirstlane_b32 s20, v4
	v_add_u32_e32 v4, 0xe000, v130
	global_load_lds_dwordx4 v[2:3], off
	v_lshl_add_u64 v[2:3], v[140:141], 0, s[16:17]
	s_mov_b32 m0, s20
	v_readfirstlane_b32 s20, v4
	global_load_lds_dwordx4 v[2:3], off
	v_lshl_add_u64 v[2:3], v[140:141], 0, s[18:19]
	s_mov_b32 m0, s20
	v_ashrrev_i32_e32 v4, 6, v6
	global_load_lds_dwordx4 v[2:3], off
	v_lshrrev_b32_e32 v5, 30, v4
	v_add_u32_e32 v5, v4, v5
	s_or_b32 s20, s62, s64
	v_bfe_u32 v2, v6, 4, 2
	v_bfe_u32 v3, v6, 1, 3
	v_and_b32_e32 v6, 0x7fffc, v5
	s_ashr_i32 s21, s20, 31
	v_sub_u32_e32 v4, v4, v6
	s_lshl_b64 s[20:21], s[20:21], 19
	v_lshlrev_b32_e32 v150, 13, v4
	v_bitop3_b32 v4, v7, v3, 3 bitop3:0x6c
	v_bitop3_b32 v2, v2, v3, 4 bitop3:0x36
	s_add_u32 s20, s34, s20
	v_lshlrev_b32_e32 v5, 12, v5
	v_lshlrev_b32_e32 v4, 3, v4
	v_lshlrev_b32_e32 v2, 3, v2
	s_addc_u32 s21, s35, s21
	v_and_b32_e32 v149, 0xffffc000, v5
	v_lshl_add_u64 v[142:143], s[20:21], 0, v[0:1]
	s_mov_b64 s[60:61], 0
	v_lshlrev_b32_e32 v151, 1, v8
	v_lshlrev_b32_e32 v152, 1, v4
	v_lshlrev_b32_e32 v153, 1, v2
	s_mov_b32 s59, 0
	s_mov_b32 s57, 0
	v_mov_b32_e32 v40, 0
	v_mov_b32_e32 v41, v131
	v_mov_b32_e32 v42, v131
	v_mov_b32_e32 v43, v131
	v_mov_b32_e32 v48, 0
	v_mov_b32_e32 v49, v131
	v_mov_b32_e32 v50, v131
	v_mov_b32_e32 v51, v131
	v_mov_b32_e32 v0, 0
	v_mov_b32_e32 v1, v131
	v_mov_b32_e32 v2, v131
	v_mov_b32_e32 v3, v131
	v_mov_b32_e32 v4, 0
	v_mov_b32_e32 v5, v131
	v_mov_b32_e32 v6, v131
	v_mov_b32_e32 v7, v131
	v_mov_b32_e32 v8, 0
	v_mov_b32_e32 v9, v131
	v_mov_b32_e32 v10, v131
	v_mov_b32_e32 v11, v131
	v_mov_b32_e32 v12, 0
	v_mov_b32_e32 v13, v131
	v_mov_b32_e32 v14, v131
	v_mov_b32_e32 v15, v131
	v_mov_b32_e32 v16, 0
	v_mov_b32_e32 v17, v131
	v_mov_b32_e32 v18, v131
	v_mov_b32_e32 v19, v131
	v_mov_b32_e32 v20, 0
	v_mov_b32_e32 v21, v131
	v_mov_b32_e32 v22, v131
	v_mov_b32_e32 v23, v131
	v_mov_b32_e32 v24, 0
	v_mov_b32_e32 v25, v131
	v_mov_b32_e32 v26, v131
	v_mov_b32_e32 v27, v131
	v_mov_b32_e32 v28, 0
	v_mov_b32_e32 v29, v131
	v_mov_b32_e32 v30, v131
	v_mov_b32_e32 v31, v131
	v_mov_b32_e32 v32, 0
	v_mov_b32_e32 v33, v131
	v_mov_b32_e32 v34, v131
	v_mov_b32_e32 v35, v131
	v_mov_b32_e32 v36, 0
	v_mov_b32_e32 v37, v131
	v_mov_b32_e32 v38, v131
	v_mov_b32_e32 v39, v131
	v_mov_b32_e32 v44, 0
	v_mov_b32_e32 v45, v131
	v_mov_b32_e32 v46, v131
	v_mov_b32_e32 v47, v131
	v_mov_b32_e32 v52, 0
	v_mov_b32_e32 v53, v131
	v_mov_b32_e32 v54, v131
	v_mov_b32_e32 v55, v131
	v_mov_b32_e32 v56, 0
	v_mov_b32_e32 v57, v131
	v_mov_b32_e32 v58, v131
	v_mov_b32_e32 v59, v131
	v_mov_b32_e32 v60, 0
	v_mov_b32_e32 v61, v131
	v_mov_b32_e32 v62, v131
	v_mov_b32_e32 v63, v131
	v_mov_b32_e32 v64, 0
	v_mov_b32_e32 v65, v131
	v_mov_b32_e32 v66, v131
	v_mov_b32_e32 v67, v131
	v_mov_b32_e32 v68, 0
	v_mov_b32_e32 v69, v131
	v_mov_b32_e32 v70, v131
	v_mov_b32_e32 v71, v131
	v_mov_b32_e32 v72, 0
	v_mov_b32_e32 v73, v131
	v_mov_b32_e32 v74, v131
	v_mov_b32_e32 v75, v131
	v_mov_b32_e32 v76, 0
	v_mov_b32_e32 v77, v131
	v_mov_b32_e32 v78, v131
	v_mov_b32_e32 v79, v131
	v_mov_b32_e32 v80, 0
	v_mov_b32_e32 v81, v131
	v_mov_b32_e32 v82, v131
	v_mov_b32_e32 v83, v131
	v_mov_b32_e32 v84, 0
	v_mov_b32_e32 v85, v131
	v_mov_b32_e32 v86, v131
	v_mov_b32_e32 v87, v131
	v_mov_b32_e32 v88, 0
	v_mov_b32_e32 v89, v131
	v_mov_b32_e32 v90, v131
	v_mov_b32_e32 v91, v131
	v_mov_b32_e32 v92, 0
	v_mov_b32_e32 v93, v131
	v_mov_b32_e32 v94, v131
	v_mov_b32_e32 v95, v131
	v_mov_b32_e32 v96, 0
	v_mov_b32_e32 v97, v131
	v_mov_b32_e32 v98, v131
	v_mov_b32_e32 v99, v131
	v_mov_b32_e32 v100, 0
	v_mov_b32_e32 v101, v131
	v_mov_b32_e32 v102, v131
	v_mov_b32_e32 v103, v131
	v_mov_b32_e32 v104, 0
	v_mov_b32_e32 v105, v131
	v_mov_b32_e32 v106, v131
	v_mov_b32_e32 v107, v131
	v_mov_b32_e32 v108, 0
	v_mov_b32_e32 v109, v131
	v_mov_b32_e32 v110, v131
	v_mov_b32_e32 v111, v131
	v_mov_b32_e32 v112, 0
	v_mov_b32_e32 v113, v131
	v_mov_b32_e32 v114, v131
	v_mov_b32_e32 v115, v131
	v_mov_b32_e32 v116, 0
	v_mov_b32_e32 v117, v131
	v_mov_b32_e32 v118, v131
	v_mov_b32_e32 v119, v131
	v_mov_b32_e32 v120, 0
	v_mov_b32_e32 v121, v131
	v_mov_b32_e32 v122, v131
	v_mov_b32_e32 v123, v131
	v_mov_b32_e32 v124, 0
	v_mov_b32_e32 v125, v131
	v_mov_b32_e32 v126, v131
	v_mov_b32_e32 v127, v131
	s_waitcnt vmcnt(0) lgkmcnt(0)
	s_barrier
	s_nop 0
	v_add3_u32 v180, v149, v151, v152
	v_add3_u32 v223, v150, v151, v152
	v_add3_u32 v222, v149, v151, v153
	v_add3_u32 v224, v150, v151, v153
	v_xor_b32_e32 v225, 0x10000, v180
	v_xor_b32_e32 v226, 0x10000, v222
	v_xor_b32_e32 v227, 0x10000, v223
	v_xor_b32_e32 v228, 0x10000, v224
	v_readfirstlane_b32 s59, v130
	ds_read_b128 v[154:157], v180
	ds_read_b128 v[158:161], v180 offset:2048
	ds_read_b128 v[162:165], v180 offset:4096
	ds_read_b128 v[166:169], v180 offset:6144
	ds_read_b128 v[190:193], v223 offset:32768
	ds_read_b128 v[194:197], v223 offset:34816
	ds_read_b128 v[198:201], v223 offset:36864
	ds_read_b128 v[202:205], v223 offset:38912
	s_mov_b32 s57, 0
	s_mov_b64 s[60:61], s[34:35]
	v_subrev_u32_e32 v178, s34, v142
	v_subrev_u32_e32 v179, s34, v140
	s_add_u32 s59, s59, 0x10000
	s_mov_b32 m0, s59
	s_add_u32 s62, s60, s22
	s_addc_u32 s63, s61, s23
	global_load_lds_dwordx4 v178, s[62:63]
	s_add_u32 m0, s59, 0x2000
	s_add_u32 s62, s60, s36
	s_addc_u32 s63, s61, s37
	global_load_lds_dwordx4 v178, s[62:63]
	s_add_u32 m0, s59, 0x4000
	s_add_u32 s62, s60, s38
	s_addc_u32 s63, s61, s39
	global_load_lds_dwordx4 v178, s[62:63]
	s_add_u32 m0, s59, 0x6000
	s_add_u32 s62, s60, s40
	s_addc_u32 s63, s61, s41
	global_load_lds_dwordx4 v178, s[62:63]
	s_add_u32 m0, s59, 0x8000
	s_add_u32 s62, s60, s42
	s_addc_u32 s63, s61, s43
	global_load_lds_dwordx4 v179, s[62:63]
	s_add_u32 m0, s59, 0xa000
	s_add_u32 s62, s60, s44
	s_addc_u32 s63, s61, s45
	global_load_lds_dwordx4 v179, s[62:63]
	s_add_u32 m0, s59, 0xc000
	s_add_u32 s62, s60, s46
	s_addc_u32 s63, s61, s47
	global_load_lds_dwordx4 v179, s[62:63]
	s_add_u32 m0, s59, 0xe000
	s_add_u32 s62, s60, s48
	s_addc_u32 s63, s61, s49
	global_load_lds_dwordx4 v179, s[62:63]
	s_branch .Lg8_entry
